# scan loader: wait after mid-chunk barrier relaxed from vmcnt(0) to vmcnt(6) (do not wait for the just-issued y stores); dead WAW waits removed
# baseline (speedup 1.0000x reference)
; #define SC_LOAD(Q, c) do { const size_t o_ = offA + (size_t)(c) * SC_TC * DR; (Q).r = *(const u32x2*)(P.SR + o_); (Q).k = *(const u32x2*)(P.SKT + o_); (Q).wr = *(const u32x2*)(P.SWR + o_); \
;         (Q).m = *(const u32x2*)(P.SREM + o_); (Q).d = *(const u32x2*)(lbase + (size_t)(c) * SC_TC * 3072); if (isv) (Q).v = *(const u32x2*)(P.SV + o_); } while (0)
; __device__ __forceinline__ void scan_item(LAS unsigned char* lds, const ScanPtrs& P, bf16* YC, int item, unsigned* half_cnt, unsigned half_expect) {
;     ...
;             if (c + 2 < NCH) SC_STORE(q0, 0); if (c + 4 < NCH) SC_LOAD(q0, c + 4);
.LBB0_761:
	s_cmpk_gt_u32 s25, 0xfd
	s_cselect_b64 s[16:17], -1, 0
	s_and_b64 vcc, exec, s[16:17]
	s_waitcnt lgkmcnt(0)
	s_barrier
	s_cbranch_vccnz .LBB0_765
	s_waitcnt vmcnt(6)
	v_cvt_f32_f16_e32 v6, v49
	v_cvt_f32_f16_e32 v11, v48
	v_cvt_f32_f16_sdwa v63, v49 dst_sel:DWORD dst_unused:UNUSED_PAD src0_sel:WORD_1
	v_cvt_f32_f16_sdwa v65, v48 dst_sel:DWORD dst_unused:UNUSED_PAD src0_sel:WORD_1
	v_sub_f32_e32 v66, 1.0, v6
	v_sub_f32_e32 v64, 1.0, v11
	v_sub_f32_e32 v67, 1.0, v63
	v_sub_f32_e32 v65, 1.0, v65
	ds_write_b128 v52, v[64:67]
	v_lshlrev_b32_e32 v64, 16, v46
	v_and_b32_e32 v65, 0xffff0000, v46
	v_lshlrev_b32_e32 v66, 16, v47
	v_and_b32_e32 v67, 0xffff0000, v47
	ds_write_b128 v52, v[64:67] offset:256
	v_lshlrev_b32_e32 v64, 16, v44
	v_and_b32_e32 v65, 0xffff0000, v44
	v_lshlrev_b32_e32 v66, 16, v45
	v_and_b32_e32 v67, 0xffff0000, v45
	ds_write_b128 v52, v[64:67] offset:512
	v_lshlrev_b32_e32 v64, 16, v42
	v_and_b32_e32 v65, 0xffff0000, v42
	v_lshlrev_b32_e32 v66, 16, v43
	v_and_b32_e32 v67, 0xffff0000, v43
	ds_write_b128 v52, v[64:67] offset:768
	v_lshlrev_b32_e32 v64, 16, v40
	v_and_b32_e32 v65, 0xffff0000, v40
	v_lshlrev_b32_e32 v66, 16, v41
	v_and_b32_e32 v67, 0xffff0000, v41
	ds_write_b128 v52, v[64:67] offset:1024
	s_and_saveexec_b64 s[18:19], s[2:3]
	v_lshlrev_b32_e32 v64, 16, v24
	v_and_b32_e32 v65, 0xffff0000, v24
	v_lshlrev_b32_e32 v66, 16, v25
	v_and_b32_e32 v67, 0xffff0000, v25
	ds_write_b128 v53, v[64:67] offset:1280
	s_or_b64 exec, exec, s[18:19]
.LBB0_765:
	s_cmpk_gt_u32 s25, 0xfb
	s_cbranch_scc1 .LBB0_741
	s_lshl_b32 s0, s25, 4
	s_add_i32 s0, s0, 64
	s_lshl_b64 s[18:19], s[0:1], 11
	v_lshl_add_u64 v[40:41], v[16:17], 0, s[18:19]
	v_lshl_add_u64 v[42:43], v[18:19], 0, s[18:19]
	v_lshl_add_u64 v[44:45], v[20:21], 0, s[18:19]
	v_lshl_add_u64 v[46:47], v[22:23], 0, s[18:19]
	global_load_dwordx2 v[40:41], v[40:41], off
	s_nop 0
	global_load_dwordx2 v[42:43], v[42:43], off
	s_nop 0
	global_load_dwordx2 v[44:45], v[44:45], off
	s_nop 0
	global_load_dwordx2 v[46:47], v[46:47], off
	v_mad_u64_u32 v[48:49], s[18:19], s0, v62, v[14:15]
	global_load_dwordx2 v[48:49], v[48:49], off
	s_and_saveexec_b64 s[18:19], s[2:3]
	s_cbranch_execz .LBB0_740
	s_lshl_b64 s[26:27], s[0:1], 10
	v_lshl_add_u64 v[24:25], s[26:27], 0, v[12:13]
	v_lshl_add_u64 v[24:25], v[24:25], 1, s[74:75]
	global_load_dwordx2 v[24:25], v[24:25], off
	s_branch .LBB0_740
